# P9 epilogue: the 128 gelu chains replaced by one in-place block of packed f32 ops (same operations, order and constants; bit-identical)
# baseline (speedup 1.0000x reference)
.LBB0_1148:
	s_mov_b32 s98, 0x3d372713
	s_mov_b32 s99, 0x3fcc422a
	v_mov_b32_e32 v146, 0xbfb8aa3b
	v_pk_mul_f32 v[136:137], v[126:127], s[98:99] op_sel_hi:[1,0]
	v_pk_mul_f32 v[138:139], v[124:125], s[98:99] op_sel_hi:[1,0]
	v_pk_mul_f32 v[142:143], v[122:123], s[98:99] op_sel_hi:[1,0]
	v_pk_mul_f32 v[148:149], v[120:121], s[98:99] op_sel_hi:[1,0]
	v_pk_fma_f32 v[136:137], v[126:127], v[136:137], 1.0 op_sel_hi:[1,1,0]
	v_pk_fma_f32 v[138:139], v[124:125], v[138:139], 1.0 op_sel_hi:[1,1,0]
	v_pk_fma_f32 v[142:143], v[122:123], v[142:143], 1.0 op_sel_hi:[1,1,0]
	v_pk_fma_f32 v[148:149], v[120:121], v[148:149], 1.0 op_sel_hi:[1,1,0]
	v_pk_mul_f32 v[136:137], v[126:127], v[136:137]
	v_pk_mul_f32 v[138:139], v[124:125], v[138:139]
	v_pk_mul_f32 v[142:143], v[122:123], v[142:143]
	v_pk_mul_f32 v[148:149], v[120:121], v[148:149]
	v_pk_mul_f32 v[136:137], v[136:137], s[98:99] op_sel:[0,1] op_sel_hi:[1,1]
	v_pk_mul_f32 v[138:139], v[138:139], s[98:99] op_sel:[0,1] op_sel_hi:[1,1]
	v_pk_mul_f32 v[142:143], v[142:143], s[98:99] op_sel:[0,1] op_sel_hi:[1,1]
	v_pk_mul_f32 v[148:149], v[148:149], s[98:99] op_sel:[0,1] op_sel_hi:[1,1]
	v_pk_mul_f32 v[136:137], v[136:137], v[146:147] op_sel_hi:[1,0]
	v_pk_mul_f32 v[138:139], v[138:139], v[146:147] op_sel_hi:[1,0]
	v_pk_mul_f32 v[142:143], v[142:143], v[146:147] op_sel_hi:[1,0]
	v_pk_mul_f32 v[148:149], v[148:149], v[146:147] op_sel_hi:[1,0]
	v_exp_f32_e32 v136, v136
	v_exp_f32_e32 v137, v137
	v_exp_f32_e32 v138, v138
	v_exp_f32_e32 v139, v139
	v_exp_f32_e32 v142, v142
	v_exp_f32_e32 v143, v143
	v_exp_f32_e32 v148, v148
	v_exp_f32_e32 v149, v149
	v_pk_add_f32 v[136:137], v[136:137], 1.0 op_sel_hi:[1,0]
	v_pk_add_f32 v[138:139], v[138:139], 1.0 op_sel_hi:[1,0]
	v_pk_add_f32 v[142:143], v[142:143], 1.0 op_sel_hi:[1,0]
	v_pk_add_f32 v[148:149], v[148:149], 1.0 op_sel_hi:[1,0]
	v_rcp_f32_e32 v136, v136
	v_rcp_f32_e32 v137, v137
	v_rcp_f32_e32 v138, v138
	v_rcp_f32_e32 v139, v139
	v_rcp_f32_e32 v142, v142
	v_rcp_f32_e32 v143, v143
	v_rcp_f32_e32 v148, v148
	v_rcp_f32_e32 v149, v149
	v_pk_mul_f32 v[126:127], v[126:127], v[136:137]
	v_pk_mul_f32 v[124:125], v[124:125], v[138:139]
	v_pk_mul_f32 v[122:123], v[122:123], v[142:143]
	v_pk_mul_f32 v[120:121], v[120:121], v[148:149]
	v_pk_mul_f32 v[136:137], v[118:119], s[98:99] op_sel_hi:[1,0]
	v_pk_mul_f32 v[138:139], v[116:117], s[98:99] op_sel_hi:[1,0]
	v_pk_mul_f32 v[142:143], v[114:115], s[98:99] op_sel_hi:[1,0]
	v_pk_mul_f32 v[148:149], v[112:113], s[98:99] op_sel_hi:[1,0]
	v_pk_fma_f32 v[136:137], v[118:119], v[136:137], 1.0 op_sel_hi:[1,1,0]
	v_pk_fma_f32 v[138:139], v[116:117], v[138:139], 1.0 op_sel_hi:[1,1,0]
	v_pk_fma_f32 v[142:143], v[114:115], v[142:143], 1.0 op_sel_hi:[1,1,0]
	v_pk_fma_f32 v[148:149], v[112:113], v[148:149], 1.0 op_sel_hi:[1,1,0]
	v_pk_mul_f32 v[136:137], v[118:119], v[136:137]
	v_pk_mul_f32 v[138:139], v[116:117], v[138:139]
	v_pk_mul_f32 v[142:143], v[114:115], v[142:143]
	v_pk_mul_f32 v[148:149], v[112:113], v[148:149]
	v_pk_mul_f32 v[136:137], v[136:137], s[98:99] op_sel:[0,1] op_sel_hi:[1,1]
	v_pk_mul_f32 v[138:139], v[138:139], s[98:99] op_sel:[0,1] op_sel_hi:[1,1]
	v_pk_mul_f32 v[142:143], v[142:143], s[98:99] op_sel:[0,1] op_sel_hi:[1,1]
	v_pk_mul_f32 v[148:149], v[148:149], s[98:99] op_sel:[0,1] op_sel_hi:[1,1]
	v_pk_mul_f32 v[136:137], v[136:137], v[146:147] op_sel_hi:[1,0]
	v_pk_mul_f32 v[138:139], v[138:139], v[146:147] op_sel_hi:[1,0]
	v_pk_mul_f32 v[142:143], v[142:143], v[146:147] op_sel_hi:[1,0]
	v_pk_mul_f32 v[148:149], v[148:149], v[146:147] op_sel_hi:[1,0]
	v_exp_f32_e32 v136, v136
	v_exp_f32_e32 v137, v137
	v_exp_f32_e32 v138, v138
	v_exp_f32_e32 v139, v139
	v_exp_f32_e32 v142, v142
	v_exp_f32_e32 v143, v143
	v_exp_f32_e32 v148, v148
	v_exp_f32_e32 v149, v149
	v_pk_add_f32 v[136:137], v[136:137], 1.0 op_sel_hi:[1,0]
	v_pk_add_f32 v[138:139], v[138:139], 1.0 op_sel_hi:[1,0]
	v_pk_add_f32 v[142:143], v[142:143], 1.0 op_sel_hi:[1,0]
	v_pk_add_f32 v[148:149], v[148:149], 1.0 op_sel_hi:[1,0]
	v_rcp_f32_e32 v136, v136
	v_rcp_f32_e32 v137, v137
	v_rcp_f32_e32 v138, v138
	v_rcp_f32_e32 v139, v139
	v_rcp_f32_e32 v142, v142
	v_rcp_f32_e32 v143, v143
	v_rcp_f32_e32 v148, v148
	v_rcp_f32_e32 v149, v149
	v_pk_mul_f32 v[118:119], v[118:119], v[136:137]
	v_pk_mul_f32 v[116:117], v[116:117], v[138:139]
	v_pk_mul_f32 v[114:115], v[114:115], v[142:143]
	v_pk_mul_f32 v[112:113], v[112:113], v[148:149]
	v_pk_mul_f32 v[136:137], v[110:111], s[98:99] op_sel_hi:[1,0]
	v_pk_mul_f32 v[138:139], v[108:109], s[98:99] op_sel_hi:[1,0]
	v_pk_mul_f32 v[142:143], v[106:107], s[98:99] op_sel_hi:[1,0]
	v_pk_mul_f32 v[148:149], v[104:105], s[98:99] op_sel_hi:[1,0]
	v_pk_fma_f32 v[136:137], v[110:111], v[136:137], 1.0 op_sel_hi:[1,1,0]
	v_pk_fma_f32 v[138:139], v[108:109], v[138:139], 1.0 op_sel_hi:[1,1,0]
	v_pk_fma_f32 v[142:143], v[106:107], v[142:143], 1.0 op_sel_hi:[1,1,0]
	v_pk_fma_f32 v[148:149], v[104:105], v[148:149], 1.0 op_sel_hi:[1,1,0]
	v_pk_mul_f32 v[136:137], v[110:111], v[136:137]
	v_pk_mul_f32 v[138:139], v[108:109], v[138:139]
	v_pk_mul_f32 v[142:143], v[106:107], v[142:143]
	v_pk_mul_f32 v[148:149], v[104:105], v[148:149]
	v_pk_mul_f32 v[136:137], v[136:137], s[98:99] op_sel:[0,1] op_sel_hi:[1,1]
	v_pk_mul_f32 v[138:139], v[138:139], s[98:99] op_sel:[0,1] op_sel_hi:[1,1]
	v_pk_mul_f32 v[142:143], v[142:143], s[98:99] op_sel:[0,1] op_sel_hi:[1,1]
	v_pk_mul_f32 v[148:149], v[148:149], s[98:99] op_sel:[0,1] op_sel_hi:[1,1]
	v_pk_mul_f32 v[136:137], v[136:137], v[146:147] op_sel_hi:[1,0]
	v_pk_mul_f32 v[138:139], v[138:139], v[146:147] op_sel_hi:[1,0]
	v_pk_mul_f32 v[142:143], v[142:143], v[146:147] op_sel_hi:[1,0]
	v_pk_mul_f32 v[148:149], v[148:149], v[146:147] op_sel_hi:[1,0]
	v_exp_f32_e32 v136, v136
	v_exp_f32_e32 v137, v137
	v_exp_f32_e32 v138, v138
	v_exp_f32_e32 v139, v139
	v_exp_f32_e32 v142, v142
	v_exp_f32_e32 v143, v143
	v_exp_f32_e32 v148, v148
	v_exp_f32_e32 v149, v149
	v_pk_add_f32 v[136:137], v[136:137], 1.0 op_sel_hi:[1,0]
	v_pk_add_f32 v[138:139], v[138:139], 1.0 op_sel_hi:[1,0]
	v_pk_add_f32 v[142:143], v[142:143], 1.0 op_sel_hi:[1,0]
	v_pk_add_f32 v[148:149], v[148:149], 1.0 op_sel_hi:[1,0]
	v_rcp_f32_e32 v136, v136
	v_rcp_f32_e32 v137, v137
	v_rcp_f32_e32 v138, v138
	v_rcp_f32_e32 v139, v139
	v_rcp_f32_e32 v142, v142
	v_rcp_f32_e32 v143, v143
	v_rcp_f32_e32 v148, v148
	v_rcp_f32_e32 v149, v149
	v_pk_mul_f32 v[110:111], v[110:111], v[136:137]
	v_pk_mul_f32 v[108:109], v[108:109], v[138:139]
	v_pk_mul_f32 v[106:107], v[106:107], v[142:143]
	v_pk_mul_f32 v[104:105], v[104:105], v[148:149]
	v_pk_mul_f32 v[136:137], v[102:103], s[98:99] op_sel_hi:[1,0]
	v_pk_mul_f32 v[138:139], v[100:101], s[98:99] op_sel_hi:[1,0]
	v_pk_mul_f32 v[142:143], v[98:99], s[98:99] op_sel_hi:[1,0]
	v_pk_mul_f32 v[148:149], v[96:97], s[98:99] op_sel_hi:[1,0]
	v_pk_fma_f32 v[136:137], v[102:103], v[136:137], 1.0 op_sel_hi:[1,1,0]
	v_pk_fma_f32 v[138:139], v[100:101], v[138:139], 1.0 op_sel_hi:[1,1,0]
	v_pk_fma_f32 v[142:143], v[98:99], v[142:143], 1.0 op_sel_hi:[1,1,0]
	v_pk_fma_f32 v[148:149], v[96:97], v[148:149], 1.0 op_sel_hi:[1,1,0]
	v_pk_mul_f32 v[136:137], v[102:103], v[136:137]
	v_pk_mul_f32 v[138:139], v[100:101], v[138:139]
	v_pk_mul_f32 v[142:143], v[98:99], v[142:143]
	v_pk_mul_f32 v[148:149], v[96:97], v[148:149]
	v_pk_mul_f32 v[136:137], v[136:137], s[98:99] op_sel:[0,1] op_sel_hi:[1,1]
	v_pk_mul_f32 v[138:139], v[138:139], s[98:99] op_sel:[0,1] op_sel_hi:[1,1]
	v_pk_mul_f32 v[142:143], v[142:143], s[98:99] op_sel:[0,1] op_sel_hi:[1,1]
	v_pk_mul_f32 v[148:149], v[148:149], s[98:99] op_sel:[0,1] op_sel_hi:[1,1]
	v_pk_mul_f32 v[136:137], v[136:137], v[146:147] op_sel_hi:[1,0]
	v_pk_mul_f32 v[138:139], v[138:139], v[146:147] op_sel_hi:[1,0]
	v_pk_mul_f32 v[142:143], v[142:143], v[146:147] op_sel_hi:[1,0]
	v_pk_mul_f32 v[148:149], v[148:149], v[146:147] op_sel_hi:[1,0]
	v_exp_f32_e32 v136, v136
	v_exp_f32_e32 v137, v137
	v_exp_f32_e32 v138, v138
	v_exp_f32_e32 v139, v139
	v_exp_f32_e32 v142, v142
	v_exp_f32_e32 v143, v143
	v_exp_f32_e32 v148, v148
	v_exp_f32_e32 v149, v149
	v_pk_add_f32 v[136:137], v[136:137], 1.0 op_sel_hi:[1,0]
	v_pk_add_f32 v[138:139], v[138:139], 1.0 op_sel_hi:[1,0]
	v_pk_add_f32 v[142:143], v[142:143], 1.0 op_sel_hi:[1,0]
	v_pk_add_f32 v[148:149], v[148:149], 1.0 op_sel_hi:[1,0]
	v_rcp_f32_e32 v136, v136
	v_rcp_f32_e32 v137, v137
	v_rcp_f32_e32 v138, v138
	v_rcp_f32_e32 v139, v139
	v_rcp_f32_e32 v142, v142
	v_rcp_f32_e32 v143, v143
	v_rcp_f32_e32 v148, v148
	v_rcp_f32_e32 v149, v149
	v_pk_mul_f32 v[102:103], v[102:103], v[136:137]
	v_pk_mul_f32 v[100:101], v[100:101], v[138:139]
	v_pk_mul_f32 v[98:99], v[98:99], v[142:143]
	v_pk_mul_f32 v[96:97], v[96:97], v[148:149]
	v_pk_mul_f32 v[136:137], v[94:95], s[98:99] op_sel_hi:[1,0]
	v_pk_mul_f32 v[138:139], v[92:93], s[98:99] op_sel_hi:[1,0]
	v_pk_mul_f32 v[142:143], v[90:91], s[98:99] op_sel_hi:[1,0]
	v_pk_mul_f32 v[148:149], v[88:89], s[98:99] op_sel_hi:[1,0]
	v_pk_fma_f32 v[136:137], v[94:95], v[136:137], 1.0 op_sel_hi:[1,1,0]
	v_pk_fma_f32 v[138:139], v[92:93], v[138:139], 1.0 op_sel_hi:[1,1,0]
	v_pk_fma_f32 v[142:143], v[90:91], v[142:143], 1.0 op_sel_hi:[1,1,0]
	v_pk_fma_f32 v[148:149], v[88:89], v[148:149], 1.0 op_sel_hi:[1,1,0]
	v_pk_mul_f32 v[136:137], v[94:95], v[136:137]
	v_pk_mul_f32 v[138:139], v[92:93], v[138:139]
	v_pk_mul_f32 v[142:143], v[90:91], v[142:143]
	v_pk_mul_f32 v[148:149], v[88:89], v[148:149]
	v_pk_mul_f32 v[136:137], v[136:137], s[98:99] op_sel:[0,1] op_sel_hi:[1,1]
	v_pk_mul_f32 v[138:139], v[138:139], s[98:99] op_sel:[0,1] op_sel_hi:[1,1]
	v_pk_mul_f32 v[142:143], v[142:143], s[98:99] op_sel:[0,1] op_sel_hi:[1,1]
	v_pk_mul_f32 v[148:149], v[148:149], s[98:99] op_sel:[0,1] op_sel_hi:[1,1]
	v_pk_mul_f32 v[136:137], v[136:137], v[146:147] op_sel_hi:[1,0]
	v_pk_mul_f32 v[138:139], v[138:139], v[146:147] op_sel_hi:[1,0]
	v_pk_mul_f32 v[142:143], v[142:143], v[146:147] op_sel_hi:[1,0]
	v_pk_mul_f32 v[148:149], v[148:149], v[146:147] op_sel_hi:[1,0]
	v_exp_f32_e32 v136, v136
	v_exp_f32_e32 v137, v137
	v_exp_f32_e32 v138, v138
	v_exp_f32_e32 v139, v139
	v_exp_f32_e32 v142, v142
	v_exp_f32_e32 v143, v143
	v_exp_f32_e32 v148, v148
	v_exp_f32_e32 v149, v149
	v_pk_add_f32 v[136:137], v[136:137], 1.0 op_sel_hi:[1,0]
	v_pk_add_f32 v[138:139], v[138:139], 1.0 op_sel_hi:[1,0]
	v_pk_add_f32 v[142:143], v[142:143], 1.0 op_sel_hi:[1,0]
	v_pk_add_f32 v[148:149], v[148:149], 1.0 op_sel_hi:[1,0]
	v_rcp_f32_e32 v136, v136
	v_rcp_f32_e32 v137, v137
	v_rcp_f32_e32 v138, v138
	v_rcp_f32_e32 v139, v139
	v_rcp_f32_e32 v142, v142
	v_rcp_f32_e32 v143, v143
	v_rcp_f32_e32 v148, v148
	v_rcp_f32_e32 v149, v149
	v_pk_mul_f32 v[94:95], v[94:95], v[136:137]
	v_pk_mul_f32 v[92:93], v[92:93], v[138:139]
	v_pk_mul_f32 v[90:91], v[90:91], v[142:143]
	v_pk_mul_f32 v[88:89], v[88:89], v[148:149]
	v_pk_mul_f32 v[136:137], v[86:87], s[98:99] op_sel_hi:[1,0]
	v_pk_mul_f32 v[138:139], v[84:85], s[98:99] op_sel_hi:[1,0]
	v_pk_mul_f32 v[142:143], v[82:83], s[98:99] op_sel_hi:[1,0]
	v_pk_mul_f32 v[148:149], v[80:81], s[98:99] op_sel_hi:[1,0]
	v_pk_fma_f32 v[136:137], v[86:87], v[136:137], 1.0 op_sel_hi:[1,1,0]
	v_pk_fma_f32 v[138:139], v[84:85], v[138:139], 1.0 op_sel_hi:[1,1,0]
	v_pk_fma_f32 v[142:143], v[82:83], v[142:143], 1.0 op_sel_hi:[1,1,0]
	v_pk_fma_f32 v[148:149], v[80:81], v[148:149], 1.0 op_sel_hi:[1,1,0]
	v_pk_mul_f32 v[136:137], v[86:87], v[136:137]
	v_pk_mul_f32 v[138:139], v[84:85], v[138:139]
	v_pk_mul_f32 v[142:143], v[82:83], v[142:143]
	v_pk_mul_f32 v[148:149], v[80:81], v[148:149]
	v_pk_mul_f32 v[136:137], v[136:137], s[98:99] op_sel:[0,1] op_sel_hi:[1,1]
	v_pk_mul_f32 v[138:139], v[138:139], s[98:99] op_sel:[0,1] op_sel_hi:[1,1]
	v_pk_mul_f32 v[142:143], v[142:143], s[98:99] op_sel:[0,1] op_sel_hi:[1,1]
	v_pk_mul_f32 v[148:149], v[148:149], s[98:99] op_sel:[0,1] op_sel_hi:[1,1]
	v_pk_mul_f32 v[136:137], v[136:137], v[146:147] op_sel_hi:[1,0]
	v_pk_mul_f32 v[138:139], v[138:139], v[146:147] op_sel_hi:[1,0]
	v_pk_mul_f32 v[142:143], v[142:143], v[146:147] op_sel_hi:[1,0]
	v_pk_mul_f32 v[148:149], v[148:149], v[146:147] op_sel_hi:[1,0]
	v_exp_f32_e32 v136, v136
	v_exp_f32_e32 v137, v137
	v_exp_f32_e32 v138, v138
	v_exp_f32_e32 v139, v139
	v_exp_f32_e32 v142, v142
	v_exp_f32_e32 v143, v143
	v_exp_f32_e32 v148, v148
	v_exp_f32_e32 v149, v149
	v_pk_add_f32 v[136:137], v[136:137], 1.0 op_sel_hi:[1,0]
	v_pk_add_f32 v[138:139], v[138:139], 1.0 op_sel_hi:[1,0]
	v_pk_add_f32 v[142:143], v[142:143], 1.0 op_sel_hi:[1,0]
	v_pk_add_f32 v[148:149], v[148:149], 1.0 op_sel_hi:[1,0]
	v_rcp_f32_e32 v136, v136
	v_rcp_f32_e32 v137, v137
	v_rcp_f32_e32 v138, v138
	v_rcp_f32_e32 v139, v139
	v_rcp_f32_e32 v142, v142
	v_rcp_f32_e32 v143, v143
	v_rcp_f32_e32 v148, v148
	v_rcp_f32_e32 v149, v149
	v_pk_mul_f32 v[86:87], v[86:87], v[136:137]
	v_pk_mul_f32 v[84:85], v[84:85], v[138:139]
	v_pk_mul_f32 v[82:83], v[82:83], v[142:143]
	v_pk_mul_f32 v[80:81], v[80:81], v[148:149]
	v_pk_mul_f32 v[136:137], v[78:79], s[98:99] op_sel_hi:[1,0]
	v_pk_mul_f32 v[138:139], v[76:77], s[98:99] op_sel_hi:[1,0]
	v_pk_mul_f32 v[142:143], v[74:75], s[98:99] op_sel_hi:[1,0]
	v_pk_mul_f32 v[148:149], v[72:73], s[98:99] op_sel_hi:[1,0]
	v_pk_fma_f32 v[136:137], v[78:79], v[136:137], 1.0 op_sel_hi:[1,1,0]
	v_pk_fma_f32 v[138:139], v[76:77], v[138:139], 1.0 op_sel_hi:[1,1,0]
	v_pk_fma_f32 v[142:143], v[74:75], v[142:143], 1.0 op_sel_hi:[1,1,0]
	v_pk_fma_f32 v[148:149], v[72:73], v[148:149], 1.0 op_sel_hi:[1,1,0]
	v_pk_mul_f32 v[136:137], v[78:79], v[136:137]
	v_pk_mul_f32 v[138:139], v[76:77], v[138:139]
	v_pk_mul_f32 v[142:143], v[74:75], v[142:143]
	v_pk_mul_f32 v[148:149], v[72:73], v[148:149]
	v_pk_mul_f32 v[136:137], v[136:137], s[98:99] op_sel:[0,1] op_sel_hi:[1,1]
	v_pk_mul_f32 v[138:139], v[138:139], s[98:99] op_sel:[0,1] op_sel_hi:[1,1]
	v_pk_mul_f32 v[142:143], v[142:143], s[98:99] op_sel:[0,1] op_sel_hi:[1,1]
	v_pk_mul_f32 v[148:149], v[148:149], s[98:99] op_sel:[0,1] op_sel_hi:[1,1]
	v_pk_mul_f32 v[136:137], v[136:137], v[146:147] op_sel_hi:[1,0]
	v_pk_mul_f32 v[138:139], v[138:139], v[146:147] op_sel_hi:[1,0]
	v_pk_mul_f32 v[142:143], v[142:143], v[146:147] op_sel_hi:[1,0]
	v_pk_mul_f32 v[148:149], v[148:149], v[146:147] op_sel_hi:[1,0]
	v_exp_f32_e32 v136, v136
	v_exp_f32_e32 v137, v137
	v_exp_f32_e32 v138, v138
	v_exp_f32_e32 v139, v139
	v_exp_f32_e32 v142, v142
	v_exp_f32_e32 v143, v143
	v_exp_f32_e32 v148, v148
	v_exp_f32_e32 v149, v149
	v_pk_add_f32 v[136:137], v[136:137], 1.0 op_sel_hi:[1,0]
	v_pk_add_f32 v[138:139], v[138:139], 1.0 op_sel_hi:[1,0]
	v_pk_add_f32 v[142:143], v[142:143], 1.0 op_sel_hi:[1,0]
	v_pk_add_f32 v[148:149], v[148:149], 1.0 op_sel_hi:[1,0]
	v_rcp_f32_e32 v136, v136
	v_rcp_f32_e32 v137, v137
	v_rcp_f32_e32 v138, v138
	v_rcp_f32_e32 v139, v139
	v_rcp_f32_e32 v142, v142
	v_rcp_f32_e32 v143, v143
	v_rcp_f32_e32 v148, v148
	v_rcp_f32_e32 v149, v149
	v_pk_mul_f32 v[78:79], v[78:79], v[136:137]
	v_pk_mul_f32 v[76:77], v[76:77], v[138:139]
	v_pk_mul_f32 v[74:75], v[74:75], v[142:143]
	v_pk_mul_f32 v[72:73], v[72:73], v[148:149]
	v_pk_mul_f32 v[136:137], v[70:71], s[98:99] op_sel_hi:[1,0]
	v_pk_mul_f32 v[138:139], v[68:69], s[98:99] op_sel_hi:[1,0]
	v_pk_mul_f32 v[142:143], v[66:67], s[98:99] op_sel_hi:[1,0]
	v_pk_mul_f32 v[148:149], v[64:65], s[98:99] op_sel_hi:[1,0]
	v_pk_fma_f32 v[136:137], v[70:71], v[136:137], 1.0 op_sel_hi:[1,1,0]
	v_pk_fma_f32 v[138:139], v[68:69], v[138:139], 1.0 op_sel_hi:[1,1,0]
	v_pk_fma_f32 v[142:143], v[66:67], v[142:143], 1.0 op_sel_hi:[1,1,0]
	v_pk_fma_f32 v[148:149], v[64:65], v[148:149], 1.0 op_sel_hi:[1,1,0]
	v_pk_mul_f32 v[136:137], v[70:71], v[136:137]
	v_pk_mul_f32 v[138:139], v[68:69], v[138:139]
	v_pk_mul_f32 v[142:143], v[66:67], v[142:143]
	v_pk_mul_f32 v[148:149], v[64:65], v[148:149]
	v_pk_mul_f32 v[136:137], v[136:137], s[98:99] op_sel:[0,1] op_sel_hi:[1,1]
	v_pk_mul_f32 v[138:139], v[138:139], s[98:99] op_sel:[0,1] op_sel_hi:[1,1]
	v_pk_mul_f32 v[142:143], v[142:143], s[98:99] op_sel:[0,1] op_sel_hi:[1,1]
	v_pk_mul_f32 v[148:149], v[148:149], s[98:99] op_sel:[0,1] op_sel_hi:[1,1]
	v_pk_mul_f32 v[136:137], v[136:137], v[146:147] op_sel_hi:[1,0]
	v_pk_mul_f32 v[138:139], v[138:139], v[146:147] op_sel_hi:[1,0]
	v_pk_mul_f32 v[142:143], v[142:143], v[146:147] op_sel_hi:[1,0]
	v_pk_mul_f32 v[148:149], v[148:149], v[146:147] op_sel_hi:[1,0]
	v_exp_f32_e32 v136, v136
	v_exp_f32_e32 v137, v137
	v_exp_f32_e32 v138, v138
	v_exp_f32_e32 v139, v139
	v_exp_f32_e32 v142, v142
	v_exp_f32_e32 v143, v143
	v_exp_f32_e32 v148, v148
	v_exp_f32_e32 v149, v149
	v_pk_add_f32 v[136:137], v[136:137], 1.0 op_sel_hi:[1,0]
	v_pk_add_f32 v[138:139], v[138:139], 1.0 op_sel_hi:[1,0]
	v_pk_add_f32 v[142:143], v[142:143], 1.0 op_sel_hi:[1,0]
	v_pk_add_f32 v[148:149], v[148:149], 1.0 op_sel_hi:[1,0]
	v_rcp_f32_e32 v136, v136
	v_rcp_f32_e32 v137, v137
	v_rcp_f32_e32 v138, v138
	v_rcp_f32_e32 v139, v139
	v_rcp_f32_e32 v142, v142
	v_rcp_f32_e32 v143, v143
	v_rcp_f32_e32 v148, v148
	v_rcp_f32_e32 v149, v149
	v_pk_mul_f32 v[70:71], v[70:71], v[136:137]
	v_pk_mul_f32 v[68:69], v[68:69], v[138:139]
	v_pk_mul_f32 v[66:67], v[66:67], v[142:143]
	v_pk_mul_f32 v[64:65], v[64:65], v[148:149]
	v_pk_mul_f32 v[136:137], v[62:63], s[98:99] op_sel_hi:[1,0]
	v_pk_mul_f32 v[138:139], v[60:61], s[98:99] op_sel_hi:[1,0]
	v_pk_mul_f32 v[142:143], v[58:59], s[98:99] op_sel_hi:[1,0]
	v_pk_mul_f32 v[148:149], v[56:57], s[98:99] op_sel_hi:[1,0]
	v_pk_fma_f32 v[136:137], v[62:63], v[136:137], 1.0 op_sel_hi:[1,1,0]
	v_pk_fma_f32 v[138:139], v[60:61], v[138:139], 1.0 op_sel_hi:[1,1,0]
	v_pk_fma_f32 v[142:143], v[58:59], v[142:143], 1.0 op_sel_hi:[1,1,0]
	v_pk_fma_f32 v[148:149], v[56:57], v[148:149], 1.0 op_sel_hi:[1,1,0]
	v_pk_mul_f32 v[136:137], v[62:63], v[136:137]
	v_pk_mul_f32 v[138:139], v[60:61], v[138:139]
	v_pk_mul_f32 v[142:143], v[58:59], v[142:143]
	v_pk_mul_f32 v[148:149], v[56:57], v[148:149]
	v_pk_mul_f32 v[136:137], v[136:137], s[98:99] op_sel:[0,1] op_sel_hi:[1,1]
	v_pk_mul_f32 v[138:139], v[138:139], s[98:99] op_sel:[0,1] op_sel_hi:[1,1]
	v_pk_mul_f32 v[142:143], v[142:143], s[98:99] op_sel:[0,1] op_sel_hi:[1,1]
	v_pk_mul_f32 v[148:149], v[148:149], s[98:99] op_sel:[0,1] op_sel_hi:[1,1]
	v_pk_mul_f32 v[136:137], v[136:137], v[146:147] op_sel_hi:[1,0]
	v_pk_mul_f32 v[138:139], v[138:139], v[146:147] op_sel_hi:[1,0]
	v_pk_mul_f32 v[142:143], v[142:143], v[146:147] op_sel_hi:[1,0]
	v_pk_mul_f32 v[148:149], v[148:149], v[146:147] op_sel_hi:[1,0]
	v_exp_f32_e32 v136, v136
	v_exp_f32_e32 v137, v137
	v_exp_f32_e32 v138, v138
	v_exp_f32_e32 v139, v139
	v_exp_f32_e32 v142, v142
	v_exp_f32_e32 v143, v143
	v_exp_f32_e32 v148, v148
	v_exp_f32_e32 v149, v149
	v_pk_add_f32 v[136:137], v[136:137], 1.0 op_sel_hi:[1,0]
	v_pk_add_f32 v[138:139], v[138:139], 1.0 op_sel_hi:[1,0]
	v_pk_add_f32 v[142:143], v[142:143], 1.0 op_sel_hi:[1,0]
	v_pk_add_f32 v[148:149], v[148:149], 1.0 op_sel_hi:[1,0]
	v_rcp_f32_e32 v136, v136
	v_rcp_f32_e32 v137, v137
	v_rcp_f32_e32 v138, v138
	v_rcp_f32_e32 v139, v139
	v_rcp_f32_e32 v142, v142
	v_rcp_f32_e32 v143, v143
	v_rcp_f32_e32 v148, v148
	v_rcp_f32_e32 v149, v149
	v_pk_mul_f32 v[62:63], v[62:63], v[136:137]
	v_pk_mul_f32 v[60:61], v[60:61], v[138:139]
	v_pk_mul_f32 v[58:59], v[58:59], v[142:143]
	v_pk_mul_f32 v[56:57], v[56:57], v[148:149]
	v_pk_mul_f32 v[136:137], v[54:55], s[98:99] op_sel_hi:[1,0]
	v_pk_mul_f32 v[138:139], v[52:53], s[98:99] op_sel_hi:[1,0]
	v_pk_mul_f32 v[142:143], v[50:51], s[98:99] op_sel_hi:[1,0]
	v_pk_mul_f32 v[148:149], v[48:49], s[98:99] op_sel_hi:[1,0]
	v_pk_fma_f32 v[136:137], v[54:55], v[136:137], 1.0 op_sel_hi:[1,1,0]
	v_pk_fma_f32 v[138:139], v[52:53], v[138:139], 1.0 op_sel_hi:[1,1,0]
	v_pk_fma_f32 v[142:143], v[50:51], v[142:143], 1.0 op_sel_hi:[1,1,0]
	v_pk_fma_f32 v[148:149], v[48:49], v[148:149], 1.0 op_sel_hi:[1,1,0]
	v_pk_mul_f32 v[136:137], v[54:55], v[136:137]
	v_pk_mul_f32 v[138:139], v[52:53], v[138:139]
	v_pk_mul_f32 v[142:143], v[50:51], v[142:143]
	v_pk_mul_f32 v[148:149], v[48:49], v[148:149]
	v_pk_mul_f32 v[136:137], v[136:137], s[98:99] op_sel:[0,1] op_sel_hi:[1,1]
	v_pk_mul_f32 v[138:139], v[138:139], s[98:99] op_sel:[0,1] op_sel_hi:[1,1]
	v_pk_mul_f32 v[142:143], v[142:143], s[98:99] op_sel:[0,1] op_sel_hi:[1,1]
	v_pk_mul_f32 v[148:149], v[148:149], s[98:99] op_sel:[0,1] op_sel_hi:[1,1]
	v_pk_mul_f32 v[136:137], v[136:137], v[146:147] op_sel_hi:[1,0]
	v_pk_mul_f32 v[138:139], v[138:139], v[146:147] op_sel_hi:[1,0]
	v_pk_mul_f32 v[142:143], v[142:143], v[146:147] op_sel_hi:[1,0]
	v_pk_mul_f32 v[148:149], v[148:149], v[146:147] op_sel_hi:[1,0]
	v_exp_f32_e32 v136, v136
	v_exp_f32_e32 v137, v137
	v_exp_f32_e32 v138, v138
	v_exp_f32_e32 v139, v139
	v_exp_f32_e32 v142, v142
	v_exp_f32_e32 v143, v143
	v_exp_f32_e32 v148, v148
	v_exp_f32_e32 v149, v149
	v_pk_add_f32 v[136:137], v[136:137], 1.0 op_sel_hi:[1,0]
	v_pk_add_f32 v[138:139], v[138:139], 1.0 op_sel_hi:[1,0]
	v_pk_add_f32 v[142:143], v[142:143], 1.0 op_sel_hi:[1,0]
	v_pk_add_f32 v[148:149], v[148:149], 1.0 op_sel_hi:[1,0]
	v_rcp_f32_e32 v136, v136
	v_rcp_f32_e32 v137, v137
	v_rcp_f32_e32 v138, v138
	v_rcp_f32_e32 v139, v139
	v_rcp_f32_e32 v142, v142
	v_rcp_f32_e32 v143, v143
	v_rcp_f32_e32 v148, v148
	v_rcp_f32_e32 v149, v149
	v_pk_mul_f32 v[54:55], v[54:55], v[136:137]
	v_pk_mul_f32 v[52:53], v[52:53], v[138:139]
	v_pk_mul_f32 v[50:51], v[50:51], v[142:143]
	v_pk_mul_f32 v[48:49], v[48:49], v[148:149]
	v_pk_mul_f32 v[136:137], v[46:47], s[98:99] op_sel_hi:[1,0]
	v_pk_mul_f32 v[138:139], v[44:45], s[98:99] op_sel_hi:[1,0]
	v_pk_mul_f32 v[142:143], v[42:43], s[98:99] op_sel_hi:[1,0]
	v_pk_mul_f32 v[148:149], v[40:41], s[98:99] op_sel_hi:[1,0]
	v_pk_fma_f32 v[136:137], v[46:47], v[136:137], 1.0 op_sel_hi:[1,1,0]
	v_pk_fma_f32 v[138:139], v[44:45], v[138:139], 1.0 op_sel_hi:[1,1,0]
	v_pk_fma_f32 v[142:143], v[42:43], v[142:143], 1.0 op_sel_hi:[1,1,0]
	v_pk_fma_f32 v[148:149], v[40:41], v[148:149], 1.0 op_sel_hi:[1,1,0]
	v_pk_mul_f32 v[136:137], v[46:47], v[136:137]
	v_pk_mul_f32 v[138:139], v[44:45], v[138:139]
	v_pk_mul_f32 v[142:143], v[42:43], v[142:143]
	v_pk_mul_f32 v[148:149], v[40:41], v[148:149]
	v_pk_mul_f32 v[136:137], v[136:137], s[98:99] op_sel:[0,1] op_sel_hi:[1,1]
	v_pk_mul_f32 v[138:139], v[138:139], s[98:99] op_sel:[0,1] op_sel_hi:[1,1]
	v_pk_mul_f32 v[142:143], v[142:143], s[98:99] op_sel:[0,1] op_sel_hi:[1,1]
	v_pk_mul_f32 v[148:149], v[148:149], s[98:99] op_sel:[0,1] op_sel_hi:[1,1]
	v_pk_mul_f32 v[136:137], v[136:137], v[146:147] op_sel_hi:[1,0]
	v_pk_mul_f32 v[138:139], v[138:139], v[146:147] op_sel_hi:[1,0]
	v_pk_mul_f32 v[142:143], v[142:143], v[146:147] op_sel_hi:[1,0]
	v_pk_mul_f32 v[148:149], v[148:149], v[146:147] op_sel_hi:[1,0]
	v_exp_f32_e32 v136, v136
	v_exp_f32_e32 v137, v137
	v_exp_f32_e32 v138, v138
	v_exp_f32_e32 v139, v139
	v_exp_f32_e32 v142, v142
	v_exp_f32_e32 v143, v143
	v_exp_f32_e32 v148, v148
	v_exp_f32_e32 v149, v149
	v_pk_add_f32 v[136:137], v[136:137], 1.0 op_sel_hi:[1,0]
	v_pk_add_f32 v[138:139], v[138:139], 1.0 op_sel_hi:[1,0]
	v_pk_add_f32 v[142:143], v[142:143], 1.0 op_sel_hi:[1,0]
	v_pk_add_f32 v[148:149], v[148:149], 1.0 op_sel_hi:[1,0]
	v_rcp_f32_e32 v136, v136
	v_rcp_f32_e32 v137, v137
	v_rcp_f32_e32 v138, v138
	v_rcp_f32_e32 v139, v139
	v_rcp_f32_e32 v142, v142
	v_rcp_f32_e32 v143, v143
	v_rcp_f32_e32 v148, v148
	v_rcp_f32_e32 v149, v149
	v_pk_mul_f32 v[46:47], v[46:47], v[136:137]
	v_pk_mul_f32 v[44:45], v[44:45], v[138:139]
	v_pk_mul_f32 v[42:43], v[42:43], v[142:143]
	v_pk_mul_f32 v[40:41], v[40:41], v[148:149]
	v_pk_mul_f32 v[136:137], v[38:39], s[98:99] op_sel_hi:[1,0]
	v_pk_mul_f32 v[138:139], v[36:37], s[98:99] op_sel_hi:[1,0]
	v_pk_mul_f32 v[142:143], v[34:35], s[98:99] op_sel_hi:[1,0]
	v_pk_mul_f32 v[148:149], v[32:33], s[98:99] op_sel_hi:[1,0]
	v_pk_fma_f32 v[136:137], v[38:39], v[136:137], 1.0 op_sel_hi:[1,1,0]
	v_pk_fma_f32 v[138:139], v[36:37], v[138:139], 1.0 op_sel_hi:[1,1,0]
	v_pk_fma_f32 v[142:143], v[34:35], v[142:143], 1.0 op_sel_hi:[1,1,0]
	v_pk_fma_f32 v[148:149], v[32:33], v[148:149], 1.0 op_sel_hi:[1,1,0]
	v_pk_mul_f32 v[136:137], v[38:39], v[136:137]
	v_pk_mul_f32 v[138:139], v[36:37], v[138:139]
	v_pk_mul_f32 v[142:143], v[34:35], v[142:143]
	v_pk_mul_f32 v[148:149], v[32:33], v[148:149]
	v_pk_mul_f32 v[136:137], v[136:137], s[98:99] op_sel:[0,1] op_sel_hi:[1,1]
	v_pk_mul_f32 v[138:139], v[138:139], s[98:99] op_sel:[0,1] op_sel_hi:[1,1]
	v_pk_mul_f32 v[142:143], v[142:143], s[98:99] op_sel:[0,1] op_sel_hi:[1,1]
	v_pk_mul_f32 v[148:149], v[148:149], s[98:99] op_sel:[0,1] op_sel_hi:[1,1]
	v_pk_mul_f32 v[136:137], v[136:137], v[146:147] op_sel_hi:[1,0]
	v_pk_mul_f32 v[138:139], v[138:139], v[146:147] op_sel_hi:[1,0]
	v_pk_mul_f32 v[142:143], v[142:143], v[146:147] op_sel_hi:[1,0]
	v_pk_mul_f32 v[148:149], v[148:149], v[146:147] op_sel_hi:[1,0]
	v_exp_f32_e32 v136, v136
	v_exp_f32_e32 v137, v137
	v_exp_f32_e32 v138, v138
	v_exp_f32_e32 v139, v139
	v_exp_f32_e32 v142, v142
	v_exp_f32_e32 v143, v143
	v_exp_f32_e32 v148, v148
	v_exp_f32_e32 v149, v149
	v_pk_add_f32 v[136:137], v[136:137], 1.0 op_sel_hi:[1,0]
	v_pk_add_f32 v[138:139], v[138:139], 1.0 op_sel_hi:[1,0]
	v_pk_add_f32 v[142:143], v[142:143], 1.0 op_sel_hi:[1,0]
	v_pk_add_f32 v[148:149], v[148:149], 1.0 op_sel_hi:[1,0]
	v_rcp_f32_e32 v136, v136
	v_rcp_f32_e32 v137, v137
	v_rcp_f32_e32 v138, v138
	v_rcp_f32_e32 v139, v139
	v_rcp_f32_e32 v142, v142
	v_rcp_f32_e32 v143, v143
	v_rcp_f32_e32 v148, v148
	v_rcp_f32_e32 v149, v149
	v_pk_mul_f32 v[38:39], v[38:39], v[136:137]
	v_pk_mul_f32 v[36:37], v[36:37], v[138:139]
	v_pk_mul_f32 v[34:35], v[34:35], v[142:143]
	v_pk_mul_f32 v[32:33], v[32:33], v[148:149]
	v_pk_mul_f32 v[136:137], v[30:31], s[98:99] op_sel_hi:[1,0]
	v_pk_mul_f32 v[138:139], v[28:29], s[98:99] op_sel_hi:[1,0]
	v_pk_mul_f32 v[142:143], v[26:27], s[98:99] op_sel_hi:[1,0]
	v_pk_mul_f32 v[148:149], v[24:25], s[98:99] op_sel_hi:[1,0]
	v_pk_fma_f32 v[136:137], v[30:31], v[136:137], 1.0 op_sel_hi:[1,1,0]
	v_pk_fma_f32 v[138:139], v[28:29], v[138:139], 1.0 op_sel_hi:[1,1,0]
	v_pk_fma_f32 v[142:143], v[26:27], v[142:143], 1.0 op_sel_hi:[1,1,0]
	v_pk_fma_f32 v[148:149], v[24:25], v[148:149], 1.0 op_sel_hi:[1,1,0]
	v_pk_mul_f32 v[136:137], v[30:31], v[136:137]
	v_pk_mul_f32 v[138:139], v[28:29], v[138:139]
	v_pk_mul_f32 v[142:143], v[26:27], v[142:143]
	v_pk_mul_f32 v[148:149], v[24:25], v[148:149]
	v_pk_mul_f32 v[136:137], v[136:137], s[98:99] op_sel:[0,1] op_sel_hi:[1,1]
	v_pk_mul_f32 v[138:139], v[138:139], s[98:99] op_sel:[0,1] op_sel_hi:[1,1]
	v_pk_mul_f32 v[142:143], v[142:143], s[98:99] op_sel:[0,1] op_sel_hi:[1,1]
	v_pk_mul_f32 v[148:149], v[148:149], s[98:99] op_sel:[0,1] op_sel_hi:[1,1]
	v_pk_mul_f32 v[136:137], v[136:137], v[146:147] op_sel_hi:[1,0]
	v_pk_mul_f32 v[138:139], v[138:139], v[146:147] op_sel_hi:[1,0]
	v_pk_mul_f32 v[142:143], v[142:143], v[146:147] op_sel_hi:[1,0]
	v_pk_mul_f32 v[148:149], v[148:149], v[146:147] op_sel_hi:[1,0]
	v_exp_f32_e32 v136, v136
	v_exp_f32_e32 v137, v137
	v_exp_f32_e32 v138, v138
	v_exp_f32_e32 v139, v139
	v_exp_f32_e32 v142, v142
	v_exp_f32_e32 v143, v143
	v_exp_f32_e32 v148, v148
	v_exp_f32_e32 v149, v149
	v_pk_add_f32 v[136:137], v[136:137], 1.0 op_sel_hi:[1,0]
	v_pk_add_f32 v[138:139], v[138:139], 1.0 op_sel_hi:[1,0]
	v_pk_add_f32 v[142:143], v[142:143], 1.0 op_sel_hi:[1,0]
	v_pk_add_f32 v[148:149], v[148:149], 1.0 op_sel_hi:[1,0]
	v_rcp_f32_e32 v136, v136
	v_rcp_f32_e32 v137, v137
	v_rcp_f32_e32 v138, v138
	v_rcp_f32_e32 v139, v139
	v_rcp_f32_e32 v142, v142
	v_rcp_f32_e32 v143, v143
	v_rcp_f32_e32 v148, v148
	v_rcp_f32_e32 v149, v149
	v_pk_mul_f32 v[30:31], v[30:31], v[136:137]
	v_pk_mul_f32 v[28:29], v[28:29], v[138:139]
	v_pk_mul_f32 v[26:27], v[26:27], v[142:143]
	v_pk_mul_f32 v[24:25], v[24:25], v[148:149]
	v_pk_mul_f32 v[136:137], v[22:23], s[98:99] op_sel_hi:[1,0]
	v_pk_mul_f32 v[138:139], v[20:21], s[98:99] op_sel_hi:[1,0]
	v_pk_mul_f32 v[142:143], v[18:19], s[98:99] op_sel_hi:[1,0]
	v_pk_mul_f32 v[148:149], v[16:17], s[98:99] op_sel_hi:[1,0]
	v_pk_fma_f32 v[136:137], v[22:23], v[136:137], 1.0 op_sel_hi:[1,1,0]
	v_pk_fma_f32 v[138:139], v[20:21], v[138:139], 1.0 op_sel_hi:[1,1,0]
	v_pk_fma_f32 v[142:143], v[18:19], v[142:143], 1.0 op_sel_hi:[1,1,0]
	v_pk_fma_f32 v[148:149], v[16:17], v[148:149], 1.0 op_sel_hi:[1,1,0]
	v_pk_mul_f32 v[136:137], v[22:23], v[136:137]
	v_pk_mul_f32 v[138:139], v[20:21], v[138:139]
	v_pk_mul_f32 v[142:143], v[18:19], v[142:143]
	v_pk_mul_f32 v[148:149], v[16:17], v[148:149]
	v_pk_mul_f32 v[136:137], v[136:137], s[98:99] op_sel:[0,1] op_sel_hi:[1,1]
	v_pk_mul_f32 v[138:139], v[138:139], s[98:99] op_sel:[0,1] op_sel_hi:[1,1]
	v_pk_mul_f32 v[142:143], v[142:143], s[98:99] op_sel:[0,1] op_sel_hi:[1,1]
	v_pk_mul_f32 v[148:149], v[148:149], s[98:99] op_sel:[0,1] op_sel_hi:[1,1]
	v_pk_mul_f32 v[136:137], v[136:137], v[146:147] op_sel_hi:[1,0]
	v_pk_mul_f32 v[138:139], v[138:139], v[146:147] op_sel_hi:[1,0]
	v_pk_mul_f32 v[142:143], v[142:143], v[146:147] op_sel_hi:[1,0]
	v_pk_mul_f32 v[148:149], v[148:149], v[146:147] op_sel_hi:[1,0]
	v_exp_f32_e32 v136, v136
	v_exp_f32_e32 v137, v137
	v_exp_f32_e32 v138, v138
	v_exp_f32_e32 v139, v139
	v_exp_f32_e32 v142, v142
	v_exp_f32_e32 v143, v143
	v_exp_f32_e32 v148, v148
	v_exp_f32_e32 v149, v149
	v_pk_add_f32 v[136:137], v[136:137], 1.0 op_sel_hi:[1,0]
	v_pk_add_f32 v[138:139], v[138:139], 1.0 op_sel_hi:[1,0]
	v_pk_add_f32 v[142:143], v[142:143], 1.0 op_sel_hi:[1,0]
	v_pk_add_f32 v[148:149], v[148:149], 1.0 op_sel_hi:[1,0]
	v_rcp_f32_e32 v136, v136
	v_rcp_f32_e32 v137, v137
	v_rcp_f32_e32 v138, v138
	v_rcp_f32_e32 v139, v139
	v_rcp_f32_e32 v142, v142
	v_rcp_f32_e32 v143, v143
	v_rcp_f32_e32 v148, v148
	v_rcp_f32_e32 v149, v149
	v_pk_mul_f32 v[22:23], v[22:23], v[136:137]
	v_pk_mul_f32 v[20:21], v[20:21], v[138:139]
	v_pk_mul_f32 v[18:19], v[18:19], v[142:143]
	v_pk_mul_f32 v[16:17], v[16:17], v[148:149]
	v_pk_mul_f32 v[136:137], v[14:15], s[98:99] op_sel_hi:[1,0]
	v_pk_mul_f32 v[138:139], v[12:13], s[98:99] op_sel_hi:[1,0]
	v_pk_mul_f32 v[142:143], v[10:11], s[98:99] op_sel_hi:[1,0]
	v_pk_mul_f32 v[148:149], v[8:9], s[98:99] op_sel_hi:[1,0]
	v_pk_fma_f32 v[136:137], v[14:15], v[136:137], 1.0 op_sel_hi:[1,1,0]
	v_pk_fma_f32 v[138:139], v[12:13], v[138:139], 1.0 op_sel_hi:[1,1,0]
	v_pk_fma_f32 v[142:143], v[10:11], v[142:143], 1.0 op_sel_hi:[1,1,0]
	v_pk_fma_f32 v[148:149], v[8:9], v[148:149], 1.0 op_sel_hi:[1,1,0]
	v_pk_mul_f32 v[136:137], v[14:15], v[136:137]
	v_pk_mul_f32 v[138:139], v[12:13], v[138:139]
	v_pk_mul_f32 v[142:143], v[10:11], v[142:143]
	v_pk_mul_f32 v[148:149], v[8:9], v[148:149]
	v_pk_mul_f32 v[136:137], v[136:137], s[98:99] op_sel:[0,1] op_sel_hi:[1,1]
	v_pk_mul_f32 v[138:139], v[138:139], s[98:99] op_sel:[0,1] op_sel_hi:[1,1]
	v_pk_mul_f32 v[142:143], v[142:143], s[98:99] op_sel:[0,1] op_sel_hi:[1,1]
	v_pk_mul_f32 v[148:149], v[148:149], s[98:99] op_sel:[0,1] op_sel_hi:[1,1]
	v_pk_mul_f32 v[136:137], v[136:137], v[146:147] op_sel_hi:[1,0]
	v_pk_mul_f32 v[138:139], v[138:139], v[146:147] op_sel_hi:[1,0]
	v_pk_mul_f32 v[142:143], v[142:143], v[146:147] op_sel_hi:[1,0]
	v_pk_mul_f32 v[148:149], v[148:149], v[146:147] op_sel_hi:[1,0]
	v_exp_f32_e32 v136, v136
	v_exp_f32_e32 v137, v137
	v_exp_f32_e32 v138, v138
	v_exp_f32_e32 v139, v139
	v_exp_f32_e32 v142, v142
	v_exp_f32_e32 v143, v143
	v_exp_f32_e32 v148, v148
	v_exp_f32_e32 v149, v149
	v_pk_add_f32 v[136:137], v[136:137], 1.0 op_sel_hi:[1,0]
	v_pk_add_f32 v[138:139], v[138:139], 1.0 op_sel_hi:[1,0]
	v_pk_add_f32 v[142:143], v[142:143], 1.0 op_sel_hi:[1,0]
	v_pk_add_f32 v[148:149], v[148:149], 1.0 op_sel_hi:[1,0]
	v_rcp_f32_e32 v136, v136
	v_rcp_f32_e32 v137, v137
	v_rcp_f32_e32 v138, v138
	v_rcp_f32_e32 v139, v139
	v_rcp_f32_e32 v142, v142
	v_rcp_f32_e32 v143, v143
	v_rcp_f32_e32 v148, v148
	v_rcp_f32_e32 v149, v149
	v_pk_mul_f32 v[14:15], v[14:15], v[136:137]
	v_pk_mul_f32 v[12:13], v[12:13], v[138:139]
	v_pk_mul_f32 v[10:11], v[10:11], v[142:143]
	v_pk_mul_f32 v[8:9], v[8:9], v[148:149]
	v_pk_mul_f32 v[136:137], v[6:7], s[98:99] op_sel_hi:[1,0]
	v_pk_mul_f32 v[138:139], v[4:5], s[98:99] op_sel_hi:[1,0]
	v_pk_mul_f32 v[142:143], v[2:3], s[98:99] op_sel_hi:[1,0]
	v_pk_mul_f32 v[148:149], v[0:1], s[98:99] op_sel_hi:[1,0]
	v_pk_fma_f32 v[136:137], v[6:7], v[136:137], 1.0 op_sel_hi:[1,1,0]
	v_pk_fma_f32 v[138:139], v[4:5], v[138:139], 1.0 op_sel_hi:[1,1,0]
	v_pk_fma_f32 v[142:143], v[2:3], v[142:143], 1.0 op_sel_hi:[1,1,0]
	v_pk_fma_f32 v[148:149], v[0:1], v[148:149], 1.0 op_sel_hi:[1,1,0]
	v_pk_mul_f32 v[136:137], v[6:7], v[136:137]
	v_pk_mul_f32 v[138:139], v[4:5], v[138:139]
	v_pk_mul_f32 v[142:143], v[2:3], v[142:143]
	v_pk_mul_f32 v[148:149], v[0:1], v[148:149]
	v_pk_mul_f32 v[136:137], v[136:137], s[98:99] op_sel:[0,1] op_sel_hi:[1,1]
	v_pk_mul_f32 v[138:139], v[138:139], s[98:99] op_sel:[0,1] op_sel_hi:[1,1]
	v_pk_mul_f32 v[142:143], v[142:143], s[98:99] op_sel:[0,1] op_sel_hi:[1,1]
	v_pk_mul_f32 v[148:149], v[148:149], s[98:99] op_sel:[0,1] op_sel_hi:[1,1]
	v_pk_mul_f32 v[136:137], v[136:137], v[146:147] op_sel_hi:[1,0]
	v_pk_mul_f32 v[138:139], v[138:139], v[146:147] op_sel_hi:[1,0]
	v_pk_mul_f32 v[142:143], v[142:143], v[146:147] op_sel_hi:[1,0]
	v_pk_mul_f32 v[148:149], v[148:149], v[146:147] op_sel_hi:[1,0]
	v_exp_f32_e32 v136, v136
	v_exp_f32_e32 v137, v137
	v_exp_f32_e32 v138, v138
	v_exp_f32_e32 v139, v139
	v_exp_f32_e32 v142, v142
	v_exp_f32_e32 v143, v143
	v_exp_f32_e32 v148, v148
	v_exp_f32_e32 v149, v149
	v_pk_add_f32 v[136:137], v[136:137], 1.0 op_sel_hi:[1,0]
	v_pk_add_f32 v[138:139], v[138:139], 1.0 op_sel_hi:[1,0]
	v_pk_add_f32 v[142:143], v[142:143], 1.0 op_sel_hi:[1,0]
	v_pk_add_f32 v[148:149], v[148:149], 1.0 op_sel_hi:[1,0]
	v_rcp_f32_e32 v136, v136
	v_rcp_f32_e32 v137, v137
	v_rcp_f32_e32 v138, v138
	v_rcp_f32_e32 v139, v139
	v_rcp_f32_e32 v142, v142
	v_rcp_f32_e32 v143, v143
	v_rcp_f32_e32 v148, v148
	v_rcp_f32_e32 v149, v149
	v_pk_mul_f32 v[6:7], v[6:7], v[136:137]
	v_pk_mul_f32 v[4:5], v[4:5], v[138:139]
	v_pk_mul_f32 v[2:3], v[2:3], v[142:143]
	v_pk_mul_f32 v[0:1], v[0:1], v[148:149]
	v_mov_b32_e32 v138, v124
	v_mov_b32_e32 v148, v125
	v_mov_b32_e32 v142, v209
	v_mov_b32_e32 v137, v254
	v_lshlrev_b32_e32 v146, 4, v137
	v_and_b32_e32 v143, 0x3ff0, v146
	v_mov_b32_e32 v149, v122
	v_ashrrev_i32_e32 v122, 4, v142
	s_lshl_b32 s43, s65, 4
	v_cvt_pk_bf16_f32 v124, v120, v121
	v_add_u32_e32 v120, v143, v122
	v_and_or_b32 v136, v142, 15, s43
	v_ashrrev_i32_e32 v121, 31, v120
	v_ashrrev_i32_e32 v137, 31, v136
	v_lshlrev_b64 v[120:121], 11, v[120:121]
	v_mov_b32_e32 v150, v126
	v_cvt_pk_bf16_f32 v125, v149, v123
	v_cvt_pk_bf16_f32 v126, v138, v148
	v_lshl_add_u64 v[138:139], s[14:15], 0, v[120:121]
	v_lshlrev_b64 v[120:121], 1, v[136:137]
	v_lshl_add_u64 v[136:137], v[138:139], 0, v[120:121]
	v_cvt_pk_bf16_f32 v127, v150, v127
	global_store_dwordx4 v[136:137], v[124:127], off
	s_nop 1
	v_mov_b32_e32 v123, v112
	v_add_u32_e32 v124, 0x80, v142
	v_mov_b32_e32 v136, v114
	v_ashrrev_i32_e32 v112, 4, v124
	v_cvt_pk_bf16_f32 v114, v123, v113
	v_cvt_pk_bf16_f32 v115, v136, v115
	v_cvt_pk_bf16_f32 v116, v116, v117
	v_cvt_pk_bf16_f32 v117, v118, v119
	v_add_u32_e32 v118, v112, v143
	v_ashrrev_i32_e32 v119, 31, v118
	v_lshlrev_b64 v[118:119], 11, v[118:119]
	v_lshl_add_u64 v[118:119], s[14:15], 0, v[118:119]
	v_lshl_add_u64 v[118:119], v[118:119], 0, v[120:121]
	global_store_dwordx4 v[118:119], v[114:117], off
	s_nop 1
	v_add_u32_e32 v114, 0x100, v146
	v_and_b32_e32 v114, 0x3ff0, v114
	v_cvt_pk_bf16_f32 v104, v104, v105
	v_cvt_pk_bf16_f32 v105, v106, v107
	v_cvt_pk_bf16_f32 v106, v108, v109
	v_add_u32_e32 v108, v114, v122
	v_ashrrev_i32_e32 v109, 31, v108
	v_lshlrev_b64 v[108:109], 11, v[108:109]
	v_lshl_add_u64 v[108:109], s[14:15], 0, v[108:109]
	v_lshl_add_u64 v[108:109], v[108:109], 0, v[120:121]
	v_cvt_pk_bf16_f32 v107, v110, v111
	global_store_dwordx4 v[108:109], v[104:107], off
	s_nop 1
	v_cvt_pk_bf16_f32 v96, v96, v97
	v_cvt_pk_bf16_f32 v97, v98, v99
	v_cvt_pk_bf16_f32 v98, v100, v101
	v_add_u32_e32 v100, v114, v112
	v_ashrrev_i32_e32 v101, 31, v100
	v_lshlrev_b64 v[100:101], 11, v[100:101]
	v_lshl_add_u64 v[100:101], s[14:15], 0, v[100:101]
	v_cvt_pk_bf16_f32 v99, v102, v103
	v_lshl_add_u64 v[100:101], v[100:101], 0, v[120:121]
	global_store_dwordx4 v[100:101], v[96:99], off
	s_nop 1
	v_add_u32_e32 v96, 0x200, v146
	v_and_b32_e32 v96, 0x3ff0, v96
	v_cvt_pk_bf16_f32 v88, v88, v89
	v_cvt_pk_bf16_f32 v89, v90, v91
	v_cvt_pk_bf16_f32 v90, v92, v93
	v_add_u32_e32 v92, v96, v122
	v_ashrrev_i32_e32 v93, 31, v92
	v_lshlrev_b64 v[92:93], 11, v[92:93]
	v_lshl_add_u64 v[92:93], s[14:15], 0, v[92:93]
	v_lshl_add_u64 v[92:93], v[92:93], 0, v[120:121]
	v_cvt_pk_bf16_f32 v91, v94, v95
	global_store_dwordx4 v[92:93], v[88:91], off
	s_nop 1
	v_cvt_pk_bf16_f32 v80, v80, v81
	v_cvt_pk_bf16_f32 v81, v82, v83
	v_cvt_pk_bf16_f32 v82, v84, v85
	v_add_u32_e32 v84, v96, v112
	v_ashrrev_i32_e32 v85, 31, v84
	v_lshlrev_b64 v[84:85], 11, v[84:85]
	v_lshl_add_u64 v[84:85], s[14:15], 0, v[84:85]
	v_cvt_pk_bf16_f32 v83, v86, v87
	v_lshl_add_u64 v[84:85], v[84:85], 0, v[120:121]
	global_store_dwordx4 v[84:85], v[80:83], off
	s_nop 1
	v_add_u32_e32 v80, 0x300, v146
	v_and_b32_e32 v80, 0x3ff0, v80
	v_cvt_pk_bf16_f32 v72, v72, v73
	v_cvt_pk_bf16_f32 v73, v74, v75
	v_cvt_pk_bf16_f32 v74, v76, v77
	v_add_u32_e32 v76, v80, v122
	v_ashrrev_i32_e32 v77, 31, v76
	v_lshlrev_b64 v[76:77], 11, v[76:77]
	v_lshl_add_u64 v[76:77], s[14:15], 0, v[76:77]
	v_lshl_add_u64 v[76:77], v[76:77], 0, v[120:121]
	v_cvt_pk_bf16_f32 v75, v78, v79
	global_store_dwordx4 v[76:77], v[72:75], off
	s_nop 1
	v_cvt_pk_bf16_f32 v64, v64, v65
	v_cvt_pk_bf16_f32 v65, v66, v67
	v_cvt_pk_bf16_f32 v66, v68, v69
	v_add_u32_e32 v68, v80, v112
	v_ashrrev_i32_e32 v69, 31, v68
	v_lshlrev_b64 v[68:69], 11, v[68:69]
	v_lshl_add_u64 v[68:69], s[14:15], 0, v[68:69]
	v_cvt_pk_bf16_f32 v67, v70, v71
	v_lshl_add_u64 v[68:69], v[68:69], 0, v[120:121]
	global_store_dwordx4 v[68:69], v[64:67], off
	s_nop 1
	v_add_u32_e32 v64, 0x800, v146
	v_and_b32_e32 v64, 0x3ff0, v64
	v_cvt_pk_bf16_f32 v56, v56, v57
	v_cvt_pk_bf16_f32 v57, v58, v59
	v_cvt_pk_bf16_f32 v58, v60, v61
	v_add_u32_e32 v60, v64, v122
	v_ashrrev_i32_e32 v61, 31, v60
	v_lshlrev_b64 v[60:61], 11, v[60:61]
	v_lshl_add_u64 v[60:61], s[14:15], 0, v[60:61]
	v_lshl_add_u64 v[60:61], v[60:61], 0, v[120:121]
	v_cvt_pk_bf16_f32 v59, v62, v63
	global_store_dwordx4 v[60:61], v[56:59], off
	s_nop 1
	v_cvt_pk_bf16_f32 v48, v48, v49
	v_cvt_pk_bf16_f32 v49, v50, v51
	v_cvt_pk_bf16_f32 v50, v52, v53
	v_add_u32_e32 v52, v64, v112
	v_ashrrev_i32_e32 v53, 31, v52
	v_lshlrev_b64 v[52:53], 11, v[52:53]
	v_lshl_add_u64 v[52:53], s[14:15], 0, v[52:53]
	v_cvt_pk_bf16_f32 v51, v54, v55
	v_lshl_add_u64 v[52:53], v[52:53], 0, v[120:121]
	global_store_dwordx4 v[52:53], v[48:51], off
	s_nop 1
	v_add_u32_e32 v48, 0x900, v146
	v_and_b32_e32 v48, 0x3ff0, v48
	v_cvt_pk_bf16_f32 v40, v40, v41
	v_cvt_pk_bf16_f32 v41, v42, v43
	v_cvt_pk_bf16_f32 v42, v44, v45
	v_add_u32_e32 v44, v48, v122
	v_ashrrev_i32_e32 v45, 31, v44
	v_lshlrev_b64 v[44:45], 11, v[44:45]
	v_lshl_add_u64 v[44:45], s[14:15], 0, v[44:45]
	v_lshl_add_u64 v[44:45], v[44:45], 0, v[120:121]
	v_cvt_pk_bf16_f32 v43, v46, v47
	global_store_dwordx4 v[44:45], v[40:43], off
	s_nop 1
	v_cvt_pk_bf16_f32 v32, v32, v33
	v_cvt_pk_bf16_f32 v33, v34, v35
	v_cvt_pk_bf16_f32 v34, v36, v37
	v_add_u32_e32 v36, v48, v112
	v_ashrrev_i32_e32 v37, 31, v36
	v_lshlrev_b64 v[36:37], 11, v[36:37]
	v_lshl_add_u64 v[36:37], s[14:15], 0, v[36:37]
	v_cvt_pk_bf16_f32 v35, v38, v39
	v_lshl_add_u64 v[36:37], v[36:37], 0, v[120:121]
	global_store_dwordx4 v[36:37], v[32:35], off
	s_nop 1
	v_add_u32_e32 v32, 0xa00, v146
	v_and_b32_e32 v32, 0x3ff0, v32
	v_cvt_pk_bf16_f32 v24, v24, v25
	v_cvt_pk_bf16_f32 v25, v26, v27
	v_cvt_pk_bf16_f32 v26, v28, v29
	v_add_u32_e32 v28, v32, v122
	v_ashrrev_i32_e32 v29, 31, v28
	v_lshlrev_b64 v[28:29], 11, v[28:29]
	v_lshl_add_u64 v[28:29], s[14:15], 0, v[28:29]
	v_lshl_add_u64 v[28:29], v[28:29], 0, v[120:121]
	v_cvt_pk_bf16_f32 v27, v30, v31
	global_store_dwordx4 v[28:29], v[24:27], off
	s_nop 1
	v_cvt_pk_bf16_f32 v16, v16, v17
	v_cvt_pk_bf16_f32 v17, v18, v19
	v_cvt_pk_bf16_f32 v18, v20, v21
	v_add_u32_e32 v20, v32, v112
	v_ashrrev_i32_e32 v21, 31, v20
	v_lshlrev_b64 v[20:21], 11, v[20:21]
	v_lshl_add_u64 v[20:21], s[14:15], 0, v[20:21]
	v_cvt_pk_bf16_f32 v19, v22, v23
	v_lshl_add_u64 v[20:21], v[20:21], 0, v[120:121]
	global_store_dwordx4 v[20:21], v[16:19], off
	s_nop 1
	v_add_u32_e32 v16, 0xb00, v146
	v_and_b32_e32 v16, 0x3ff0, v16
	v_cvt_pk_bf16_f32 v8, v8, v9
	v_cvt_pk_bf16_f32 v9, v10, v11
	v_cvt_pk_bf16_f32 v10, v12, v13
	v_add_u32_e32 v12, v16, v122
	v_ashrrev_i32_e32 v13, 31, v12
	v_lshlrev_b64 v[12:13], 11, v[12:13]
	v_lshl_add_u64 v[12:13], s[14:15], 0, v[12:13]
	v_lshl_add_u64 v[12:13], v[12:13], 0, v[120:121]
	v_cvt_pk_bf16_f32 v11, v14, v15
	global_store_dwordx4 v[12:13], v[8:11], off
	s_nop 1
	v_cvt_pk_bf16_f32 v0, v0, v1
	v_cvt_pk_bf16_f32 v1, v2, v3
	v_cvt_pk_bf16_f32 v2, v4, v5
	v_add_u32_e32 v4, v16, v112
	v_ashrrev_i32_e32 v5, 31, v4
	v_lshlrev_b64 v[4:5], 11, v[4:5]
	v_lshl_add_u64 v[4:5], s[14:15], 0, v[4:5]
	v_lshl_add_u64 v[4:5], v[4:5], 0, v[120:121]
	s_and_b64 vcc, exec, s[4:5]
	v_cvt_pk_bf16_f32 v3, v6, v7
	global_store_dwordx4 v[4:5], v[0:3], off
	s_nop 1
	s_cbranch_vccnz .LBB0_1151
	s_andn2_b64 vcc, exec, s[12:13]
	s_cbranch_vccnz .LBB0_1141
	s_barrier
	s_branch .LBB0_1141
